# ATTN fast tail: the pad slot before each PV MFMA pair now holds the next chunk's first scale-and-offset VALU instead of s_nop (3 per step)
# baseline (speedup 1.0000x reference)
.Lfa_norescale:
	v_fmamk_f32 v0, v0, 0x3fb8aa3b, v36
	v_fmamk_f32 v1, v1, 0x3fb8aa3b, v36
	v_fmamk_f32 v2, v2, 0x3fb8aa3b, v36
	v_fmamk_f32 v3, v3, 0x3fb8aa3b, v36
	v_fmamk_f32 v4, v4, 0x3fb8aa3b, v36
	v_fmamk_f32 v5, v5, 0x3fb8aa3b, v36
	v_fmamk_f32 v6, v6, 0x3fb8aa3b, v36
	v_fmamk_f32 v7, v7, 0x3fb8aa3b, v36
	v_exp_f32_e32 v0, v0
	v_exp_f32_e32 v1, v1
	v_add_f32_e32 v37, v0, v37
	v_exp_f32_e32 v2, v2
	v_add_f32_e32 v37, v1, v37
	v_exp_f32_e32 v3, v3
	v_add_f32_e32 v37, v2, v37
	v_exp_f32_e32 v4, v4
	v_add_f32_e32 v37, v3, v37
	v_exp_f32_e32 v5, v5
	v_add_f32_e32 v37, v4, v37
	v_exp_f32_e32 v6, v6
	v_add_f32_e32 v37, v5, v37
	v_exp_f32_e32 v7, v7
	v_add_f32_e32 v37, v6, v37
	s_nop 0
	v_add_f32_e32 v37, v7, v37
	v_cvt_pk_bf16_f32 v0, v0, v1
	v_cvt_pk_bf16_f32 v1, v2, v3
	v_cvt_pk_bf16_f32 v2, v4, v5
	v_cvt_pk_bf16_f32 v3, v6, v7
	s_waitcnt lgkmcnt(14)
	v_fmamk_f32 v8, v8, 0x3fb8aa3b, v36
	v_mfma_f32_32x32x16_bf16 v[64:79], v[134:137], v[0:3], v[64:79]
	s_waitcnt lgkmcnt(12)
	v_mfma_f32_32x32x16_bf16 v[48:63], v[138:141], v[0:3], v[48:63]
	v_fmamk_f32 v9, v9, 0x3fb8aa3b, v36
	v_fmamk_f32 v10, v10, 0x3fb8aa3b, v36
	v_fmamk_f32 v11, v11, 0x3fb8aa3b, v36
	v_fmamk_f32 v12, v12, 0x3fb8aa3b, v36
	v_fmamk_f32 v13, v13, 0x3fb8aa3b, v36
	v_fmamk_f32 v14, v14, 0x3fb8aa3b, v36
	v_fmamk_f32 v15, v15, 0x3fb8aa3b, v36
	v_exp_f32_e32 v8, v8
	v_exp_f32_e32 v9, v9
	v_add_f32_e32 v37, v8, v37
	v_exp_f32_e32 v10, v10
	v_add_f32_e32 v37, v9, v37
	v_exp_f32_e32 v11, v11
	v_add_f32_e32 v37, v10, v37
	v_exp_f32_e32 v12, v12
	v_add_f32_e32 v37, v11, v37
	v_exp_f32_e32 v13, v13
	v_add_f32_e32 v37, v12, v37
	v_exp_f32_e32 v14, v14
	v_add_f32_e32 v37, v13, v37
	v_exp_f32_e32 v15, v15
	v_add_f32_e32 v37, v14, v37
	s_nop 0
	v_add_f32_e32 v37, v15, v37
	v_cvt_pk_bf16_f32 v8, v8, v9
	v_cvt_pk_bf16_f32 v9, v10, v11
	v_cvt_pk_bf16_f32 v10, v12, v13
	v_cvt_pk_bf16_f32 v11, v14, v15
	s_waitcnt lgkmcnt(10)
	v_fmamk_f32 v16, v16, 0x3fb8aa3b, v36
	v_mfma_f32_32x32x16_bf16 v[64:79], v[142:145], v[8:11], v[64:79]
	s_waitcnt lgkmcnt(8)
	v_mfma_f32_32x32x16_bf16 v[48:63], v[146:149], v[8:11], v[48:63]
	v_fmamk_f32 v17, v17, 0x3fb8aa3b, v36
	v_fmamk_f32 v18, v18, 0x3fb8aa3b, v36
	v_fmamk_f32 v19, v19, 0x3fb8aa3b, v36
	v_fmamk_f32 v20, v20, 0x3fb8aa3b, v36
	v_fmamk_f32 v21, v21, 0x3fb8aa3b, v36
	v_fmamk_f32 v22, v22, 0x3fb8aa3b, v36
	v_fmamk_f32 v23, v23, 0x3fb8aa3b, v36
	v_exp_f32_e32 v16, v16
	v_exp_f32_e32 v17, v17
	v_add_f32_e32 v37, v16, v37
	v_exp_f32_e32 v18, v18
	v_add_f32_e32 v37, v17, v37
	v_exp_f32_e32 v19, v19
	v_add_f32_e32 v37, v18, v37
	v_exp_f32_e32 v20, v20
	v_add_f32_e32 v37, v19, v37
	v_exp_f32_e32 v21, v21
	v_add_f32_e32 v37, v20, v37
	v_exp_f32_e32 v22, v22
	v_add_f32_e32 v37, v21, v37
	v_exp_f32_e32 v23, v23
	v_add_f32_e32 v37, v22, v37
	s_nop 0
	v_add_f32_e32 v37, v23, v37
	v_cvt_pk_bf16_f32 v16, v16, v17
	v_cvt_pk_bf16_f32 v17, v18, v19
	v_cvt_pk_bf16_f32 v18, v20, v21
	v_cvt_pk_bf16_f32 v19, v22, v23
	s_waitcnt lgkmcnt(6)
	v_fmamk_f32 v24, v24, 0x3fb8aa3b, v36
	v_mfma_f32_32x32x16_bf16 v[64:79], v[236:239], v[16:19], v[64:79]
	s_waitcnt lgkmcnt(4)
	v_mfma_f32_32x32x16_bf16 v[48:63], v[240:243], v[16:19], v[48:63]
	v_fmamk_f32 v25, v25, 0x3fb8aa3b, v36
	v_fmamk_f32 v26, v26, 0x3fb8aa3b, v36
	v_fmamk_f32 v27, v27, 0x3fb8aa3b, v36
	v_fmamk_f32 v28, v28, 0x3fb8aa3b, v36
	v_fmamk_f32 v29, v29, 0x3fb8aa3b, v36
	v_fmamk_f32 v30, v30, 0x3fb8aa3b, v36
	v_fmamk_f32 v31, v31, 0x3fb8aa3b, v36
	v_exp_f32_e32 v24, v24
	v_exp_f32_e32 v25, v25
	v_add_f32_e32 v37, v24, v37
	v_exp_f32_e32 v26, v26
	v_add_f32_e32 v37, v25, v37
	v_exp_f32_e32 v27, v27
	v_add_f32_e32 v37, v26, v37
	v_exp_f32_e32 v28, v28
	v_add_f32_e32 v37, v27, v37
	v_exp_f32_e32 v29, v29
	v_add_f32_e32 v37, v28, v37
	v_exp_f32_e32 v30, v30
	v_add_f32_e32 v37, v29, v37
	v_exp_f32_e32 v31, v31
	v_add_f32_e32 v37, v30, v37
	s_nop 0
	v_add_f32_e32 v37, v31, v37
	v_cvt_pk_bf16_f32 v24, v24, v25
	v_cvt_pk_bf16_f32 v25, v26, v27
	v_cvt_pk_bf16_f32 v26, v28, v29
	v_cvt_pk_bf16_f32 v27, v30, v31
	s_waitcnt lgkmcnt(2)
	s_nop 0
	v_mfma_f32_32x32x16_bf16 v[64:79], v[244:247], v[24:27], v[64:79]
	s_waitcnt lgkmcnt(0)
	v_mfma_f32_32x32x16_bf16 v[48:63], v[248:251], v[24:27], v[48:63]
	v_fmac_f32_e32 v37, v121, v34
	v_mov_b32_e32 v123, v33
	v_mov_b32_e32 v121, v37
	s_branch .LBB0_1470
